# P4 writes H column tiles in descending pn order so that the first K-tiles P5 reads are the ones most recently written (still in the XCD L2)
# baseline (speedup 1.0000x reference)
; #define PG8_STAGE(bufoff, gbase, voff) do { _Pragma("unroll") for (int _i = 0; _i < 2; ++_i) \
;         __builtin_amdgcn_global_load_lds((const unsigned*)((const char*)(gbase) + (voff)[_i]), (PG8_LAS unsigned*)(lds + (bufoff) + ldsw + _i * 8192), 16, 0, 0); } while (0)
; #define PG8_WAIT_V(n) asm volatile("s_waitcnt vmcnt(" #n ")" ::: "memory")
; #define PG8_BAR __builtin_amdgcn_s_barrier()
;     __host__ __device__ bool next(int i, Unit& u) const {
;         const long L = (long)i * G + c; if (L >= nwg) return false;
;         int wgid = (int)L; { const int q = nwg / NXCD, r = nwg % NXCD, xcd = wgid % NXCD, off = wgid / NXCD; wgid = (xcd < r ? xcd * (q + 1) : r * (q + 1) + (xcd - r) * q) + off; }
;         const int nig = WGM * nN, gid = wgid / nig, fm = gid * WGM, gsz = (nM - fm) < WGM ? (nM - fm) : WGM;
;         u.pm = fm + ((wgid % nig) % gsz); u.pn = (wgid % nig) / gsz; return true;
;     }
; template <class Epi, class Sched, bool ALIGN_EPI = false, bool SP2 = false>
; __device__ __forceinline__ void gemm_phase(PG8_LAS unsigned char* lds, const Gemm g, const Sched& S, const Epi& E) {
;     ...
;     const char* cA = (const char*)g.A + (size_t)cur.pm * tstep; const char* cB = (const char*)g.Bt + (size_t)cur.pn * tstep;
;     S.a_ready(cur);
;     if constexpr (SP2) {
;         PG8_STAGE(PG8_SB(0, 0), cB, voffB); PG8_STAGE(PG8_SB(0, 1), cB + hstep, voffB); PG8_STAGE(PG8_SA(0, 0), cA, voffA); PG8_STAGE(PG8_SA(0, 1), cA + hstep, voffA);
;         if (wr == 1) PG8_BAR;
;         PG8_WAIT_V(2); PG8_BAR;
;         PG8_STAGE(PG8_SB(1, 0), cB + kstep, voffB); PG8_STAGE(PG8_SA(1, 0), cA + kstep, voffA); PG8_STAGE(PG8_SB(1, 1), cB + hstep + kstep, voffB);
;         PG8_WAIT_V(6); PG8_BAR;
;     } else {
;         PG8_STAGE(PG8_SB(0, 0), cB, voffB); PG8_STAGE(PG8_SA(0, 0), cA, voffA); PG8_STAGE(PG8_SB(0, 1), cB + hstep, voffB); PG8_STAGE(PG8_SA(0, 1), cA + hstep, voffA);
;         if (wr == 1) PG8_BAR;
;         PG8_WAIT_V(4); PG8_BAR;
.LBB0_969:
	s_ashr_i32 s2, s1, 3
	v_readlane_b32 s6, v251, 4
	v_readlane_b32 s7, v251, 5
	s_add_u32 s1, s6, 0xba00000
	s_addc_u32 s33, s7, 0
	s_add_i32 s2, s4, s2
	s_mul_hi_i32 s4, s2, 0x2e8ba2e9
	s_lshr_b32 s5, s4, 31
	s_ashr_i32 s4, s4, 5
	s_add_i32 s4, s4, s5
	s_lshl_b32 s6, s4, 3
	s_sub_i32 s5, 0x42, s6
	s_mulk_i32 s4, 0xb0
	s_min_u32 s7, s5, 8
	s_sub_i32 s10, s2, s4
	s_sext_i32_i16 s2, s10
	v_cvt_f32_ubyte0_e32 v2, s7
	v_cvt_f32_i32_e32 v1, s2
	s_waitcnt lgkmcnt(0)
	v_rcp_iflag_f32_e32 v3, v2
	s_lshr_b32 s28, s36, 6
	s_ashr_i32 s2, s2, 30
	s_lshr_b32 s3, s36, 8
	v_mul_f32_e32 v3, v1, v3
	v_trunc_f32_e32 v3, v3
	v_fma_f32 v1, -v3, v2, v1
	v_cvt_i32_f32_e32 v3, v3
	s_lshl_b32 s46, s28, 10
	s_or_b32 s2, s2, 1
	v_cmp_ge_f32_e64 s[4:5], |v1|, v2
	s_and_b64 s[4:5], s[4:5], exec
	s_cselect_b32 s2, s2, 0
	v_readfirstlane_b32 s4, v3
	s_add_i32 s2, s4, s2
	s_mul_i32 s4, s2, s7
	s_sub_i32 s4, s10, s4
	s_sext_i32_i16 s4, s4
	s_add_i32 s4, s6, s4
	s_ashr_i32 s5, s4, 31
	s_sub_i32 s2, 21, s2
	s_bfe_i64 s[6:7], s[2:3], 0x100000
	s_lshl_b64 s[12:13], s[4:5], 19
	s_lshl_b64 s[6:7], s[6:7], 19
	s_add_u32 s44, s8, s6
	v_mov_b32_e32 v133, 0
	v_lshlrev_b32_e32 v130, 4, v0
	s_addc_u32 s45, s9, s7
	s_add_i32 s47, s46, 0
	v_mov_b32_e32 v131, v133
	s_add_i32 m0, s47, 0x10000
	v_lshl_add_u64 v[2:3], s[44:45], 0, v[130:131]
	s_mov_b64 s[6:7], 0x2000
	global_load_lds_dwordx4 v130, s[44:45]
	v_lshl_add_u64 v[4:5], v[2:3], 0, s[6:7]
	s_add_i32 m0, s47, 0x12000
	s_mov_b64 s[10:11], 0x40000
	global_load_lds_dwordx4 v[4:5], off
	s_add_i32 m0, s47, 0x14000
	v_lshl_add_u64 v[4:5], v[2:3], 0, s[10:11]
	global_load_lds_dwordx4 v[4:5], off
	s_add_i32 m0, s47, 0x16000
	s_mov_b64 s[14:15], 0x42000
	s_add_u32 s12, s1, s12
	v_lshl_add_u64 v[4:5], v[2:3], 0, s[14:15]
	s_addc_u32 s13, s33, s13
	global_load_lds_dwordx4 v[4:5], off
	v_lshl_add_u64 v[4:5], s[12:13], 0, v[130:131]
	s_mov_b32 m0, s47
	s_add_i32 s52, s47, 0x2000
	global_load_lds_dwordx4 v130, s[12:13]
	v_lshl_add_u64 v[6:7], v[4:5], 0, s[6:7]
	s_mov_b32 m0, s52
	s_add_i32 s53, s47, 0x4000
	global_load_lds_dwordx4 v[6:7], off
	v_lshl_add_u64 v[6:7], v[4:5], 0, s[10:11]
	s_mov_b32 m0, s53
	s_add_i32 s54, s47, 0x6000
	global_load_lds_dwordx4 v[6:7], off
	v_lshl_add_u64 v[6:7], v[4:5], 0, s[14:15]
	s_mov_b32 m0, s54
	s_cmp_eq_u32 s3, 1
	global_load_lds_dwordx4 v[6:7], off
	s_cselect_b64 s[16:17], -1, 0
	s_cmp_lg_u32 s3, 1
	s_mov_b32 s55, 0
	s_cbranch_scc1 .LBB0_971
	s_barrier

; #define PG8_STAGE(bufoff, gbase, voff) do { _Pragma("unroll") for (int _i = 0; _i < 2; ++_i) \
;         __builtin_amdgcn_global_load_lds((const unsigned*)((const char*)(gbase) + (voff)[_i]), (PG8_LAS unsigned*)(lds + (bufoff) + ldsw + _i * 8192), 16, 0, 0); } while (0)
; #define PG8_LDA(dst, b, h) do { _Pragma("unroll") for (int m = 0; m < 4; ++m) _Pragma("unroll") for (int k = 0; k < 2; ++k) dst[m][k] = *(const PG8_LAS bf16x8*)(lds + PG8_SA(b, h) + aoff + m * 2048 + k * 1024); } while (0)
; #define PG8_LDB(dst, b, h) do { _Pragma("unroll") for (int n = 0; n < 2; ++n) _Pragma("unroll") for (int k = 0; k < 2; ++k) dst[n][k] = *(const PG8_LAS bf16x8*)(lds + PG8_SB(b, h) + boff + n * 2048 + k * 1024); } while (0)
; #define PG8_MMA(ai, bj, At, Bt) do { __builtin_amdgcn_s_setprio(1); _Pragma("unroll") for (int m = 0; m < 4; ++m) _Pragma("unroll") for (int n = 0; n < 2; ++n) _Pragma("unroll") for (int k = 0; k < 2; ++k) \
;         acc[ai][bj][m][n] = __builtin_amdgcn_mfma_f32_16x16x32_bf16(Bt[n][k], At[m][k], acc[ai][bj][m][n], 0, 0, 0); __builtin_amdgcn_s_setprio(0); } while (0)
; #define PG8_WAIT_V(n) asm volatile("s_waitcnt vmcnt(" #n ")" ::: "memory")
; #define PG8_WAIT_L(n) asm volatile("s_waitcnt lgkmcnt(" #n ")" ::: "memory")
; template <class Epi, class Sched, bool ALIGN_EPI = false, bool SP2 = false>
; __device__ __forceinline__ void gemm_phase(PG8_LAS unsigned char* lds, const Gemm g, const Sched& S, const Epi& E) {
;     ...
;     for (;;) {
;         const bool has_next = S.next(ui + 1, nxt);
;         const char* nA = has_next ? (const char*)g.A + (size_t)nxt.pm * tstep : cA; const char* nB = has_next ? (const char*)g.Bt + (size_t)nxt.pn * tstep : cB;
;         for (int t = 0; t < nt; t += 2) {
;             const bool last = (t == nt - 2);
;             const char* a1 = cA + (size_t)(t + 1) * kstep;
;             const char* a2 = last ? nA : cA + (size_t)(t + 2) * kstep; const char* b2 = last ? nB : cB + (size_t)(t + 2) * kstep;
;             const char* a3 = a2 + kstep; const char* b3 = b2 + kstep;
;             if (last && has_next) S.a_ready(nxt);
;             if constexpr (SP2) {
;             PG8_LDB(B0, 0, 0); PG8_LDB(B1, 0, 1); PG8_SCHED; PG8_LDA(At, 0, 0); PG8_STAGE(PG8_SA(1, 1), a1 + hstep, voffA);
;             PG8_WAIT_V(8); PG8_WAIT_L(0); PG8_BAR; PG8_MMA(0, 0, At, B0); PG8_MMA(0, 1, At, B1); PG8_BAR; PG8_SCHED;
.LBB0_980:
	s_sub_i32 s36, 21, s36
	s_ashr_i32 s39, s38, 31
	s_lshl_b64 s[40:41], s[38:39], 19
	s_add_u32 s40, s1, s40
	s_addc_u32 s41, s33, s41
	s_and_b64 s[42:43], s[2:3], exec
	s_cselect_b32 s39, s41, s13
	s_cselect_b32 s48, s40, s12
	s_ashr_i32 s37, s36, 31
	s_lshl_b64 s[42:43], s[36:37], 19
	s_add_u32 s42, s8, s42
	s_addc_u32 s43, s9, s43
	s_and_b64 s[50:51], s[2:3], exec
	s_cselect_b32 s37, s43, s45
	s_cselect_b32 s49, s42, s44
	s_add_u32 s12, s12, 0x44000
	s_addc_u32 s13, s13, 0
	s_add_u32 s44, s44, 0x8000
	s_addc_u32 s45, s45, 0
	s_mov_b32 s50, -2
	ds_read_b128 v[138:141], v144
	ds_read_b128 v[150:153], v144 offset:1024
	ds_read_b128 v[154:157], v144 offset:2048
	ds_read_b128 v[158:161], v144 offset:3072
	ds_read_b128 v[162:165], v145
	ds_read_b128 v[166:169], v145 offset:1024
	ds_read_b128 v[170:173], v145 offset:2048
	ds_read_b128 v[174:177], v145 offset:3072
	s_add_u32 s51, s12, 0xfffc4000
	s_addc_u32 s67, s13, -1
	s_cmp_eq_u32 s50, 12
	s_cselect_b32 s69, s39, s67
	s_cselect_b32 s68, s48, s51
	s_cselect_b32 s71, s37, s45
	s_cselect_b32 s70, s49, s44
	v_lshl_add_u64 v[198:199], s[12:13], 0, v[130:131]
	s_add_i32 m0, s47, 0xc000
	ds_read_b128 v[178:181], v146
	ds_read_b128 v[182:185], v146 offset:1024
	ds_read_b128 v[186:189], v146 offset:2048
	ds_read_b128 v[190:193], v146 offset:3072
	ds_read_b128 v[194:197], v146 offset:4096
	ds_read_b128 v[202:205], v146 offset:5120
	ds_read_b128 v[206:209], v146 offset:6144
	ds_read_b128 v[210:213], v146 offset:7168
	global_load_lds_dwordx4 v[198:199], off
	v_lshl_add_u64 v[198:199], v[198:199], 0, s[6:7]
	s_add_i32 m0, s47, 0xe000
	s_nop 0
	global_load_lds_dwordx4 v[198:199], off
	s_waitcnt vmcnt(8)
	s_waitcnt lgkmcnt(0)
	s_barrier
	s_setprio 1
	s_waitcnt lgkmcnt(0)
	v_mfma_f32_16x16x32_bf16 v[118:121], v[138:141], v[178:181], 0
	v_mfma_f32_16x16x32_bf16 v[114:117], v[154:157], v[178:181], 0
	v_mfma_f32_16x16x32_bf16 v[102:105], v[138:141], v[186:189], 0
	v_mfma_f32_16x16x32_bf16 v[98:101], v[154:157], v[186:189], 0
	v_mfma_f32_16x16x32_bf16 v[86:89], v[138:141], v[194:197], 0
	v_mfma_f32_16x16x32_bf16 v[82:85], v[154:157], v[194:197], 0
	v_mfma_f32_16x16x32_bf16 v[70:73], v[138:141], v[206:209], 0
	v_mfma_f32_16x16x32_bf16 v[66:69], v[154:157], v[206:209], 0
	v_mfma_f32_16x16x32_bf16 v[118:121], v[150:153], v[182:185], v[118:121]
	v_mfma_f32_16x16x32_bf16 v[114:117], v[158:161], v[182:185], v[114:117]
	v_mfma_f32_16x16x32_bf16 v[102:105], v[150:153], v[190:193], v[102:105]
	v_mfma_f32_16x16x32_bf16 v[98:101], v[158:161], v[190:193], v[98:101]
	v_mfma_f32_16x16x32_bf16 v[86:89], v[150:153], v[202:205], v[86:89]
	v_mfma_f32_16x16x32_bf16 v[82:85], v[158:161], v[202:205], v[82:85]
	v_mfma_f32_16x16x32_bf16 v[70:73], v[150:153], v[210:213], v[70:73]
	v_mfma_f32_16x16x32_bf16 v[66:69], v[158:161], v[210:213], v[66:69]
	s_setprio 0
	s_setprio 1
	v_mfma_f32_16x16x32_bf16 v[126:129], v[162:165], v[178:181], 0
	v_mfma_f32_16x16x32_bf16 v[122:125], v[170:173], v[178:181], 0
	v_mfma_f32_16x16x32_bf16 v[110:113], v[162:165], v[186:189], 0
	v_mfma_f32_16x16x32_bf16 v[106:109], v[170:173], v[186:189], 0
	v_mfma_f32_16x16x32_bf16 v[94:97], v[162:165], v[194:197], 0
	v_mfma_f32_16x16x32_bf16 v[90:93], v[170:173], v[194:197], 0
	v_mfma_f32_16x16x32_bf16 v[78:81], v[162:165], v[206:209], 0
	v_mfma_f32_16x16x32_bf16 v[74:77], v[170:173], v[206:209], 0
	v_mfma_f32_16x16x32_bf16 v[126:129], v[166:169], v[182:185], v[126:129]
	v_mfma_f32_16x16x32_bf16 v[122:125], v[174:177], v[182:185], v[122:125]
	v_mfma_f32_16x16x32_bf16 v[110:113], v[166:169], v[190:193], v[110:113]
	v_mfma_f32_16x16x32_bf16 v[106:109], v[174:177], v[190:193], v[106:109]
	v_mfma_f32_16x16x32_bf16 v[94:97], v[166:169], v[202:205], v[94:97]
	v_mfma_f32_16x16x32_bf16 v[90:93], v[174:177], v[202:205], v[90:93]
	v_mfma_f32_16x16x32_bf16 v[78:81], v[166:169], v[210:213], v[78:81]
	v_mfma_f32_16x16x32_bf16 v[74:77], v[174:177], v[210:213], v[74:77]
	s_setprio 0
	s_barrier
	s_add_i32 s51, s64, s46
	v_lshl_add_u64 v[198:199], s[70:71], 0, v[130:131]
	s_mov_b32 m0, s51
	ds_read_b128 v[178:181], v146 offset:16384
	ds_read_b128 v[182:185], v146 offset:17408
	ds_read_b128 v[186:189], v146 offset:18432
	ds_read_b128 v[190:193], v146 offset:19456
	ds_read_b128 v[194:197], v146 offset:20480
	ds_read_b128 v[202:205], v146 offset:21504
	ds_read_b128 v[206:209], v146 offset:22528
	ds_read_b128 v[210:213], v146 offset:23552
	global_load_lds_dwordx4 v[198:199], off
	v_lshl_add_u64 v[214:215], v[198:199], 0, s[6:7]
	s_add_i32 m0, s51, 0x2000
	s_add_i32 s51, s65, s46
	global_load_lds_dwordx4 v[214:215], off
	v_lshl_add_u64 v[214:215], v[198:199], 0, s[10:11]
	s_mov_b32 m0, s51
	s_nop 0
	global_load_lds_dwordx4 v[214:215], off
	v_lshl_add_u64 v[214:215], v[198:199], 0, s[14:15]
	s_add_i32 m0, s51, 0x2000
	s_nop 0
	global_load_lds_dwordx4 v[214:215], off
	v_lshl_add_u64 v[214:215], s[68:69], 0, v[130:131]
	s_mov_b32 m0, s47
	v_lshl_add_u64 v[216:217], v[214:215], 0, s[6:7]
	global_load_lds_dwordx4 v[214:215], off
	s_mov_b32 m0, s52
	s_nop 0
	global_load_lds_dwordx4 v[216:217], off
	s_waitcnt vmcnt(8)
	s_waitcnt lgkmcnt(0)
	s_barrier
; #define PG8_STAGE(bufoff, gbase, voff) do { _Pragma("unroll") for (int _i = 0; _i < 2; ++_i) \
;         __builtin_amdgcn_global_load_lds((const unsigned*)((const char*)(gbase) + (voff)[_i]), (PG8_LAS unsigned*)(lds + (bufoff) + ldsw + _i * 8192), 16, 0, 0); } while (0)
; #define PG8_LDA(dst, b, h) do { _Pragma("unroll") for (int m = 0; m < 4; ++m) _Pragma("unroll") for (int k = 0; k < 2; ++k) dst[m][k] = *(const PG8_LAS bf16x8*)(lds + PG8_SA(b, h) + aoff + m * 2048 + k * 1024); } while (0)
; #define PG8_LDB(dst, b, h) do { _Pragma("unroll") for (int n = 0; n < 2; ++n) _Pragma("unroll") for (int k = 0; k < 2; ++k) dst[n][k] = *(const PG8_LAS bf16x8*)(lds + PG8_SB(b, h) + boff + n * 2048 + k * 1024); } while (0)
; #define PG8_MMA(ai, bj, At, Bt) do { __builtin_amdgcn_s_setprio(1); _Pragma("unroll") for (int m = 0; m < 4; ++m) _Pragma("unroll") for (int n = 0; n < 2; ++n) _Pragma("unroll") for (int k = 0; k < 2; ++k) \
;         acc[ai][bj][m][n] = __builtin_amdgcn_mfma_f32_16x16x32_bf16(Bt[n][k], At[m][k], acc[ai][bj][m][n], 0, 0, 0); __builtin_amdgcn_s_setprio(0); } while (0)
; #define PG8_WAIT_V(n) asm volatile("s_waitcnt vmcnt(" #n ")" ::: "memory")
; #define PG8_WAIT_L(n) asm volatile("s_waitcnt lgkmcnt(" #n ")" ::: "memory")
; #define PG8_BAR __builtin_amdgcn_s_barrier()
; #define PG8_SCHED __builtin_amdgcn_sched_barrier(0)
; template <class Epi, class Sched, bool ALIGN_EPI = false, bool SP2 = false>
; __device__ __forceinline__ void gemm_phase(PG8_LAS unsigned char* lds, const Gemm g, const Sched& S, const Epi& E) {
;     ...
;             PG8_WAIT_V(8); PG8_WAIT_L(0); PG8_BAR; PG8_MMA(0, 0, At, B0); PG8_MMA(0, 1, At, B1); PG8_BAR; PG8_SCHED;
;             PG8_LDA(At, 0, 1); PG8_STAGE(PG8_SB(0, 0), b2, voffB); PG8_STAGE(PG8_SB(0, 1), b2 + hstep, voffB); PG8_STAGE(PG8_SA(0, 0), a2, voffA);
;             PG8_WAIT_V(8); PG8_WAIT_L(0); PG8_BAR; PG8_MMA(1, 0, At, B0); PG8_MMA(1, 1, At, B1); PG8_BAR; PG8_SCHED;
;             PG8_LDB(B0, 1, 0); PG8_LDB(B1, 1, 1); PG8_SCHED; PG8_LDA(At, 1, 0); PG8_STAGE(PG8_SA(0, 1), a2 + hstep, voffA);
;             PG8_WAIT_V(8); PG8_WAIT_L(0); PG8_BAR; PG8_MMA(0, 0, At, B0); PG8_MMA(0, 1, At, B1); PG8_BAR; PG8_SCHED;
	s_setprio 1
	s_waitcnt lgkmcnt(0)
	v_mfma_f32_16x16x32_bf16 v[54:57], v[138:141], v[178:181], 0
	v_mfma_f32_16x16x32_bf16 v[50:53], v[154:157], v[178:181], 0
	v_mfma_f32_16x16x32_bf16 v[38:41], v[138:141], v[186:189], 0
	v_mfma_f32_16x16x32_bf16 v[34:37], v[154:157], v[186:189], 0
	v_mfma_f32_16x16x32_bf16 v[22:25], v[138:141], v[194:197], 0
	v_mfma_f32_16x16x32_bf16 v[18:21], v[154:157], v[194:197], 0
	v_mfma_f32_16x16x32_bf16 v[6:9], v[138:141], v[206:209], 0
	v_mfma_f32_16x16x32_bf16 v[2:5], v[154:157], v[206:209], 0
	v_mfma_f32_16x16x32_bf16 v[54:57], v[150:153], v[182:185], v[54:57]
	v_mfma_f32_16x16x32_bf16 v[50:53], v[158:161], v[182:185], v[50:53]
	v_mfma_f32_16x16x32_bf16 v[38:41], v[150:153], v[190:193], v[38:41]
	v_mfma_f32_16x16x32_bf16 v[34:37], v[158:161], v[190:193], v[34:37]
	v_mfma_f32_16x16x32_bf16 v[22:25], v[150:153], v[202:205], v[22:25]
	v_mfma_f32_16x16x32_bf16 v[18:21], v[158:161], v[202:205], v[18:21]
	v_mfma_f32_16x16x32_bf16 v[6:9], v[150:153], v[210:213], v[6:9]
	v_mfma_f32_16x16x32_bf16 v[2:5], v[158:161], v[210:213], v[2:5]
	s_setprio 0
	s_setprio 1
	v_mfma_f32_16x16x32_bf16 v[62:65], v[162:165], v[178:181], 0
	v_mfma_f32_16x16x32_bf16 v[58:61], v[170:173], v[178:181], 0
	v_mfma_f32_16x16x32_bf16 v[46:49], v[162:165], v[186:189], 0
	v_mfma_f32_16x16x32_bf16 v[42:45], v[170:173], v[186:189], 0
	v_mfma_f32_16x16x32_bf16 v[30:33], v[162:165], v[194:197], 0
	v_mfma_f32_16x16x32_bf16 v[26:29], v[170:173], v[194:197], 0
	v_mfma_f32_16x16x32_bf16 v[14:17], v[162:165], v[206:209], 0
	v_mfma_f32_16x16x32_bf16 v[10:13], v[170:173], v[206:209], 0
	v_mfma_f32_16x16x32_bf16 v[62:65], v[166:169], v[182:185], v[62:65]
	v_mfma_f32_16x16x32_bf16 v[58:61], v[174:177], v[182:185], v[58:61]
	v_mfma_f32_16x16x32_bf16 v[46:49], v[166:169], v[190:193], v[46:49]
	v_mfma_f32_16x16x32_bf16 v[42:45], v[174:177], v[190:193], v[42:45]
	v_mfma_f32_16x16x32_bf16 v[30:33], v[166:169], v[202:205], v[30:33]
	v_mfma_f32_16x16x32_bf16 v[26:29], v[174:177], v[202:205], v[26:29]
	v_mfma_f32_16x16x32_bf16 v[14:17], v[166:169], v[210:213], v[14:17]
	v_mfma_f32_16x16x32_bf16 v[10:13], v[174:177], v[210:213], v[10:13]
	s_setprio 0
	s_barrier
	s_add_i32 s51, 0, 0x18000
	v_add_u32_e32 v132, s51, v143
	s_add_i32 s67, 0, 0x1c000
	ds_read_b128 v[138:141], v132
	ds_read_b128 v[150:153], v132 offset:1024
	ds_read_b128 v[154:157], v132 offset:2048
	ds_read_b128 v[158:161], v132 offset:3072
	v_add_u32_e32 v132, s67, v143
	ds_read_b128 v[162:165], v132
	ds_read_b128 v[166:169], v132 offset:1024
	ds_read_b128 v[170:173], v132 offset:2048
	ds_read_b128 v[174:177], v132 offset:3072
	s_mov_b32 m0, s53
	v_lshl_add_u64 v[216:217], v[214:215], 0, s[10:11]
	ds_read_b128 v[178:181], v146 offset:32768
	ds_read_b128 v[182:185], v146 offset:33792
	ds_read_b128 v[186:189], v146 offset:34816
	ds_read_b128 v[190:193], v146 offset:35840
	ds_read_b128 v[194:197], v146 offset:36864
	ds_read_b128 v[202:205], v146 offset:37888
	ds_read_b128 v[206:209], v146 offset:38912
	ds_read_b128 v[210:213], v146 offset:39936
	global_load_lds_dwordx4 v[216:217], off
	v_lshl_add_u64 v[216:217], v[214:215], 0, s[14:15]
	s_mov_b32 m0, s54
	s_nop 0
	global_load_lds_dwordx4 v[216:217], off
	s_waitcnt vmcnt(8)
	s_waitcnt lgkmcnt(0)
	s_barrier
	s_setprio 1
	s_waitcnt lgkmcnt(0)
	v_mfma_f32_16x16x32_bf16 v[118:121], v[138:141], v[178:181], v[118:121]
	v_mfma_f32_16x16x32_bf16 v[114:117], v[154:157], v[178:181], v[114:117]
	v_mfma_f32_16x16x32_bf16 v[102:105], v[138:141], v[186:189], v[102:105]
	v_mfma_f32_16x16x32_bf16 v[98:101], v[154:157], v[186:189], v[98:101]
	v_mfma_f32_16x16x32_bf16 v[86:89], v[138:141], v[194:197], v[86:89]
	v_mfma_f32_16x16x32_bf16 v[82:85], v[154:157], v[194:197], v[82:85]
	v_mfma_f32_16x16x32_bf16 v[70:73], v[138:141], v[206:209], v[70:73]
	v_mfma_f32_16x16x32_bf16 v[66:69], v[154:157], v[206:209], v[66:69]
	v_mfma_f32_16x16x32_bf16 v[118:121], v[150:153], v[182:185], v[118:121]
	v_mfma_f32_16x16x32_bf16 v[114:117], v[158:161], v[182:185], v[114:117]
	v_mfma_f32_16x16x32_bf16 v[102:105], v[150:153], v[190:193], v[102:105]
	v_mfma_f32_16x16x32_bf16 v[98:101], v[158:161], v[190:193], v[98:101]
	v_mfma_f32_16x16x32_bf16 v[86:89], v[150:153], v[202:205], v[86:89]
	v_mfma_f32_16x16x32_bf16 v[82:85], v[158:161], v[202:205], v[82:85]
	v_mfma_f32_16x16x32_bf16 v[70:73], v[150:153], v[210:213], v[70:73]
	v_mfma_f32_16x16x32_bf16 v[66:69], v[158:161], v[210:213], v[66:69]
	s_setprio 0
	s_setprio 1
	v_mfma_f32_16x16x32_bf16 v[126:129], v[162:165], v[178:181], v[126:129]
	v_mfma_f32_16x16x32_bf16 v[122:125], v[170:173], v[178:181], v[122:125]
	v_mfma_f32_16x16x32_bf16 v[110:113], v[162:165], v[186:189], v[110:113]
	v_mfma_f32_16x16x32_bf16 v[106:109], v[170:173], v[186:189], v[106:109]
	v_mfma_f32_16x16x32_bf16 v[94:97], v[162:165], v[194:197], v[94:97]
	v_mfma_f32_16x16x32_bf16 v[90:93], v[170:173], v[194:197], v[90:93]
	v_mfma_f32_16x16x32_bf16 v[78:81], v[162:165], v[206:209], v[78:81]
	v_mfma_f32_16x16x32_bf16 v[74:77], v[170:173], v[206:209], v[74:77]
	v_mfma_f32_16x16x32_bf16 v[126:129], v[166:169], v[182:185], v[126:129]
	v_mfma_f32_16x16x32_bf16 v[122:125], v[174:177], v[182:185], v[122:125]
	v_mfma_f32_16x16x32_bf16 v[110:113], v[166:169], v[190:193], v[110:113]
	v_mfma_f32_16x16x32_bf16 v[106:109], v[174:177], v[190:193], v[106:109]
	v_mfma_f32_16x16x32_bf16 v[94:97], v[166:169], v[202:205], v[94:97]
	v_mfma_f32_16x16x32_bf16 v[90:93], v[174:177], v[202:205], v[90:93]
	v_mfma_f32_16x16x32_bf16 v[78:81], v[166:169], v[210:213], v[78:81]
	v_mfma_f32_16x16x32_bf16 v[74:77], v[174:177], v[210:213], v[74:77]
	s_setprio 0
	s_barrier
; #define PG8_STAGE(bufoff, gbase, voff) do { _Pragma("unroll") for (int _i = 0; _i < 2; ++_i) \
;         __builtin_amdgcn_global_load_lds((const unsigned*)((const char*)(gbase) + (voff)[_i]), (PG8_LAS unsigned*)(lds + (bufoff) + ldsw + _i * 8192), 16, 0, 0); } while (0)
; #define PG8_LDA(dst, b, h) do { _Pragma("unroll") for (int m = 0; m < 4; ++m) _Pragma("unroll") for (int k = 0; k < 2; ++k) dst[m][k] = *(const PG8_LAS bf16x8*)(lds + PG8_SA(b, h) + aoff + m * 2048 + k * 1024); } while (0)
; #define PG8_MMA(ai, bj, At, Bt) do { __builtin_amdgcn_s_setprio(1); _Pragma("unroll") for (int m = 0; m < 4; ++m) _Pragma("unroll") for (int n = 0; n < 2; ++n) _Pragma("unroll") for (int k = 0; k < 2; ++k) \
;         acc[ai][bj][m][n] = __builtin_amdgcn_mfma_f32_16x16x32_bf16(Bt[n][k], At[m][k], acc[ai][bj][m][n], 0, 0, 0); __builtin_amdgcn_s_setprio(0); } while (0)
; #define PG8_WAIT_V(n) asm volatile("s_waitcnt vmcnt(" #n ")" ::: "memory")
; #define PG8_WAIT_L(n) asm volatile("s_waitcnt lgkmcnt(" #n ")" ::: "memory")
; #define PG8_BAR __builtin_amdgcn_s_barrier()
; #define PG8_SCHED __builtin_amdgcn_sched_barrier(0)
; template <class Epi, class Sched, bool ALIGN_EPI = false, bool SP2 = false>
; __device__ __forceinline__ void gemm_phase(PG8_LAS unsigned char* lds, const Gemm g, const Sched& S, const Epi& E) {
;     ...
;         for (int t = 0; t < nt; t += 2) {
;             const bool last = (t == nt - 2);
;             const char* a1 = cA + (size_t)(t + 1) * kstep;
;             const char* a2 = last ? nA : cA + (size_t)(t + 2) * kstep; const char* b2 = last ? nB : cB + (size_t)(t + 2) * kstep;
;     ...
;             PG8_LDA(At, 1, 1); PG8_STAGE(PG8_SB(1, 0), b3, voffB); PG8_STAGE(PG8_SB(1, 1), b3 + hstep, voffB); PG8_STAGE(PG8_SA(1, 0), a3, voffA);
;             PG8_WAIT_V(8); PG8_WAIT_L(0); PG8_BAR; PG8_MMA(1, 0, At, B0); PG8_MMA(1, 1, At, B1); PG8_BAR; PG8_SCHED;
	s_add_i32 s51, s51, s46
	v_lshl_add_u64 v[216:217], v[198:199], 0, s[18:19]
	s_mov_b32 m0, s51
	ds_read_b128 v[178:181], v146 offset:49152
	ds_read_b128 v[182:185], v146 offset:50176
	ds_read_b128 v[186:189], v146 offset:51200
	ds_read_b128 v[190:193], v146 offset:52224
	ds_read_b128 v[194:197], v146 offset:53248
	ds_read_b128 v[202:205], v146 offset:54272
	ds_read_b128 v[206:209], v146 offset:55296
	ds_read_b128 v[210:213], v146 offset:56320
	global_load_lds_dwordx4 v[216:217], off
	v_lshl_add_u64 v[216:217], v[198:199], 0, s[20:21]
	s_add_i32 m0, s51, 0x2000
	s_add_i32 s51, s67, s46
	global_load_lds_dwordx4 v[216:217], off
	v_lshl_add_u64 v[216:217], v[198:199], 0, s[22:23]
	s_mov_b32 m0, s51
	v_lshl_add_u64 v[198:199], v[198:199], 0, s[24:25]
	global_load_lds_dwordx4 v[216:217], off
	s_add_i32 m0, s51, 0x2000
	s_nop 0
	global_load_lds_dwordx4 v[198:199], off
	v_lshl_add_u64 v[198:199], v[214:215], 0, s[18:19]
	s_mov_b32 m0, s56
	s_nop 0
	global_load_lds_dwordx4 v[198:199], off
	v_lshl_add_u64 v[198:199], v[214:215], 0, s[20:21]
	s_mov_b32 m0, s57
	s_nop 0
	global_load_lds_dwordx4 v[198:199], off
	s_waitcnt vmcnt(8)
	s_waitcnt lgkmcnt(0)
	s_barrier
	s_setprio 1
	s_waitcnt lgkmcnt(0)
	v_mfma_f32_16x16x32_bf16 v[54:57], v[138:141], v[178:181], v[54:57]
	v_mfma_f32_16x16x32_bf16 v[50:53], v[154:157], v[178:181], v[50:53]
	v_mfma_f32_16x16x32_bf16 v[38:41], v[138:141], v[186:189], v[38:41]
	v_mfma_f32_16x16x32_bf16 v[34:37], v[154:157], v[186:189], v[34:37]
	v_mfma_f32_16x16x32_bf16 v[22:25], v[138:141], v[194:197], v[22:25]
	v_mfma_f32_16x16x32_bf16 v[18:21], v[154:157], v[194:197], v[18:21]
	v_mfma_f32_16x16x32_bf16 v[6:9], v[138:141], v[206:209], v[6:9]
	v_mfma_f32_16x16x32_bf16 v[2:5], v[154:157], v[206:209], v[2:5]
	v_mfma_f32_16x16x32_bf16 v[54:57], v[150:153], v[182:185], v[54:57]
	v_mfma_f32_16x16x32_bf16 v[50:53], v[158:161], v[182:185], v[50:53]
	v_mfma_f32_16x16x32_bf16 v[38:41], v[150:153], v[190:193], v[38:41]
	v_mfma_f32_16x16x32_bf16 v[34:37], v[158:161], v[190:193], v[34:37]
	v_mfma_f32_16x16x32_bf16 v[22:25], v[150:153], v[202:205], v[22:25]
	v_mfma_f32_16x16x32_bf16 v[18:21], v[158:161], v[202:205], v[18:21]
	v_mfma_f32_16x16x32_bf16 v[6:9], v[150:153], v[210:213], v[6:9]
	v_mfma_f32_16x16x32_bf16 v[2:5], v[158:161], v[210:213], v[2:5]
	s_setprio 0
	s_setprio 1
	v_mfma_f32_16x16x32_bf16 v[62:65], v[162:165], v[178:181], v[62:65]
	v_mfma_f32_16x16x32_bf16 v[58:61], v[170:173], v[178:181], v[58:61]
	v_mfma_f32_16x16x32_bf16 v[46:49], v[162:165], v[186:189], v[46:49]
	v_mfma_f32_16x16x32_bf16 v[42:45], v[170:173], v[186:189], v[42:45]
	v_mfma_f32_16x16x32_bf16 v[30:33], v[162:165], v[194:197], v[30:33]
	v_mfma_f32_16x16x32_bf16 v[26:29], v[170:173], v[194:197], v[26:29]
	v_mfma_f32_16x16x32_bf16 v[14:17], v[162:165], v[206:209], v[14:17]
	v_mfma_f32_16x16x32_bf16 v[10:13], v[170:173], v[206:209], v[10:13]
	v_mfma_f32_16x16x32_bf16 v[62:65], v[166:169], v[182:185], v[62:65]
	v_mfma_f32_16x16x32_bf16 v[58:61], v[174:177], v[182:185], v[58:61]
	v_mfma_f32_16x16x32_bf16 v[46:49], v[166:169], v[190:193], v[46:49]
	v_mfma_f32_16x16x32_bf16 v[42:45], v[174:177], v[190:193], v[42:45]
	v_mfma_f32_16x16x32_bf16 v[30:33], v[166:169], v[202:205], v[30:33]
	v_mfma_f32_16x16x32_bf16 v[26:29], v[174:177], v[202:205], v[26:29]
	v_mfma_f32_16x16x32_bf16 v[14:17], v[166:169], v[210:213], v[14:17]
	v_mfma_f32_16x16x32_bf16 v[10:13], v[174:177], v[210:213], v[10:13]
	s_setprio 0
	s_barrier
	s_add_i32 s50, s50, 2
	s_add_u32 s12, s12, 0x8000
	s_addc_u32 s13, s13, 0
	s_add_u32 s44, s44, 0x8000
	s_addc_u32 s45, s45, 0
	s_cmp_gt_u32 s50, 13
	s_cbranch_scc0 .LBB0_981
